# static s_setprio 1 for waves 0-3 (mirror of the waves 4-7 A/B), per-phase flips removed
# baseline (speedup 1.0000x reference)
; #define LAS __attribute__((address_space(3)))
; __global__ void __launch_bounds__(NTHR) hybrid_encoder_fwd(Params P) {
;     extern __shared__ __attribute__((aligned(16))) unsigned char lds_raw[];
;     LAS unsigned char* lds = (LAS unsigned char*)lds_raw;
;     cg::grid_group grid = cg::this_grid();
;     if (threadIdx.x == 0) { *(volatile LAS unsigned*)(lds + LDS_XB) = 0u; *(volatile LAS unsigned*)(lds + LDS_XB + 4) = 0u; }
;     __syncthreads();
;     const XcdBarrier xb = xcd_barrier_post((unsigned*)P.ws, (volatile LAS unsigned*)(lds + LDS_XB));
;     const int tid = threadIdx.x, lane = tid & 63, wid = __builtin_amdgcn_readfirstlane(tid >> 6);
_Z18hybrid_encoder_fwd6Params:
	s_load_dwordx2 s[96:97], s[0:1], 0xb0
	s_load_dwordx4 s[4:7], s[0:1], 0xa0
	s_load_dwordx8 s[12:19], s[0:1], 0x80
	s_load_dword s3, s[0:1], 0xc8
	s_load_dwordx2 s[94:95], s[0:1], 0xc0
	v_and_b32_e32 v200, 0x3ff, v0
	s_waitcnt lgkmcnt(0)
	v_readfirstlane_b32 s98, v200
	s_lshr_b32 s98, s98, 6
	s_cmp_ge_u32 s98, 4
	s_cbranch_scc1 .Lprio_done
	s_setprio 1
